# loop barriers: L1 invalidate (buffer_inv sc1) issued by wave 1 at arrival, overlapping the counter round trips, instead of after the release
# speedup vs baseline: 1.5385x; 1.0142x over previous
.LBB0_665:
	s_waitcnt vmcnt(0)
	s_waitcnt lgkmcnt(0)
	s_barrier
	v_readfirstlane_b32 s2, v0
	s_lshr_b32 s2, s2, 6
	s_cmp_lg_u32 s2, 1
	s_cbranch_scc1 .LFB_b1_noinv
	buffer_inv sc1
	s_waitcnt vmcnt(0)
.LFB_b1_noinv:
	s_mov_b64 s[0:1], exec
	v_readlane_b32 s2, v244, 4
	v_readlane_b32 s3, v244, 5
	s_and_b64 s[2:3], s[0:1], s[2:3]
	s_mov_b64 exec, s[2:3]
	s_cbranch_execz .LBB0_717
	v_readlane_b32 s4, v243, 10
	v_readlane_b32 s5, v243, 11
	v_readlane_b32 s2, v242, 40
	s_waitcnt vmcnt(0) expcnt(0) lgkmcnt(0)
	ds_read_b32 v4, v155 offset:16
	ds_read_b32 v2, v155 offset:20
	v_mov_b32_e32 v5, 1
	s_mul_i32 s2, s2, 3
	s_add_i32 s3, s2, 2
	s_add_i32 s2, s2, 1
	global_atomic_add v5, v155, v5, s[4:5] sc0
	s_add_u32 s6, s4, 0x2240
	s_addc_u32 s7, s5, 0
	s_mov_b32 s10, 0
	s_waitcnt lgkmcnt(0)
	v_mul_lo_u32 v6, v4, s3
	v_mul_lo_u32 v7, v2, s2
	s_waitcnt vmcnt(0)
	v_add_u32_e32 v5, 1, v5
	v_cmp_ne_u32_e32 vcc, v5, v6
	s_cbranch_vccnz .LFB_b1_poll
	s_mov_b64 s[12:13], exec
	s_mov_b64 exec, 0xffff
	v_mbcnt_lo_u32_b32 v8, -1, 0
	v_mov_b32_e32 v9, 1
	v_lshlrev_b32_e32 v8, 8, v8
	v_add_u32_e32 v8, 0x3640, v8
	global_atomic_add v8, v9, s[96:97]
	s_mov_b64 exec, s[12:13]
.LFB_b1_poll:
	global_load_dword v5, v155, s[6:7] sc1
	s_waitcnt vmcnt(0)
	v_cmp_ge_u32_e32 vcc, v5, v7
	s_cbranch_vccnz .LFB_b1_done
	s_sleep 1
	s_add_i32 s10, s10, 1
	s_cmp_lt_u32 s10, 0x40000
	s_cbranch_scc1 .LFB_b1_poll
.LFB_b1_done:
	s_waitcnt vmcnt(0)
.LBB0_717:
	s_or_b64 exec, exec, s[0:1]
	v_readlane_b32 s0, v243, 22
	v_readlane_b32 s1, v243, 23
	s_andn2_b64 vcc, exec, s[0:1]
	s_waitcnt lgkmcnt(0)
	s_barrier
	s_cbranch_vccnz .LBB0_743
	v_mov_b32_e32 v2, v0
	s_movk_i32 s0, 0xba0
	v_mov_b32_e32 v70, 0
	v_cmp_gt_i32_e32 vcc, s0, v2
	v_mov_b32_e32 v66, 0
	v_mov_b32_e32 v67, 0
	v_mov_b32_e32 v68, 0
	v_mov_b32_e32 v69, 0
	s_and_saveexec_b64 s[0:1], vcc
	s_cbranch_execz .LBB0_722
	s_mov_b32 s2, 0x2aaaaaab
	v_mul_hi_i32 v3, v2, s2
	v_lshrrev_b32_e32 v4, 31, v3
	v_ashrrev_i32_e32 v3, 3, v3
	v_add_u32_e32 v3, v3, v4
	v_subrev_u32_e32 v4, 30, v3
	v_readlane_b32 s2, v243, 24
	v_mov_b32_e32 v69, 0
	v_mov_b32_e32 v68, 0
	v_cmp_lt_i32_e32 vcc, s2, v4
	v_mov_b32_e32 v67, 0
	v_mov_b32_e32 v66, 0
	s_and_saveexec_b64 s[2:3], vcc
	s_cbranch_execz .LBB0_721
	v_readlane_b32 s4, v243, 25
	s_nop 1
	v_add_u32_e32 v4, s4, v4
	s_movk_i32 s4, 0xffd0
	v_ashrrev_i32_e32 v5, 31, v4
	v_mul_lo_u32 v3, v3, s4
	v_lshlrev_b64 v[4:5], 12, v[4:5]
	v_add_lshl_u32 v6, v3, v2, 3
	v_lshl_add_u64 v[4:5], s[60:61], 0, v[4:5]
	v_ashrrev_i32_e32 v7, 31, v6
	v_lshl_add_u64 v[4:5], v[6:7], 1, v[4:5]
	global_load_dwordx4 v[66:69], v[4:5], off

.LFB_b2_noinv:
	s_mov_b64 s[0:1], exec
	v_readlane_b32 s2, v244, 4
	v_readlane_b32 s3, v244, 5
	s_and_b64 s[2:3], s[0:1], s[2:3]
	s_mov_b64 exec, s[2:3]
	s_cbranch_execz .LBB0_915
	v_readlane_b32 s4, v243, 10
	v_readlane_b32 s5, v243, 11
	v_readlane_b32 s2, v242, 40
	s_waitcnt vmcnt(0) expcnt(0) lgkmcnt(0)
	ds_read_b32 v4, v155 offset:16
	ds_read_b32 v2, v155 offset:20
	v_mov_b32_e32 v5, 1
	s_mul_i32 s2, s2, 3
	s_add_i32 s3, s2, 3
	s_add_i32 s2, s2, 2
	global_atomic_add v5, v155, v5, s[4:5] sc0
	s_add_u32 s6, s4, 0x2240
	s_addc_u32 s7, s5, 0
	s_mov_b32 s10, 0
	s_waitcnt lgkmcnt(0)
	v_mul_lo_u32 v6, v4, s3
	v_mul_lo_u32 v7, v2, s2
	s_waitcnt vmcnt(0)
	v_add_u32_e32 v5, 1, v5
	v_cmp_ne_u32_e32 vcc, v5, v6
	s_cbranch_vccnz .LFB_b2_poll
	buffer_wbl2 sc1
	s_waitcnt vmcnt(0)
	s_mov_b64 s[12:13], exec
	s_mov_b64 exec, 0xffff
	v_mbcnt_lo_u32_b32 v8, -1, 0
	v_mov_b32_e32 v9, 1
	v_lshlrev_b32_e32 v8, 8, v8
	v_add_u32_e32 v8, 0x3640, v8
	global_atomic_add v8, v9, s[96:97]
	s_mov_b64 exec, s[12:13]
.LFB_b2_poll:
	global_load_dword v5, v155, s[6:7] sc1
	s_waitcnt vmcnt(0)
	v_cmp_ge_u32_e32 vcc, v5, v7
	s_cbranch_vccnz .LFB_b2_done
	s_sleep 1
	s_add_i32 s10, s10, 1
	s_cmp_lt_u32 s10, 0x40000
	s_cbranch_scc1 .LFB_b2_poll
.LFB_b2_done:
	s_waitcnt vmcnt(0)
.LBB0_915:
	s_or_b64 exec, exec, s[0:1]
	v_readlane_b32 s2, v244, 9
	v_readlane_b32 s3, v244, 10
	s_andn2_b64 vcc, exec, s[2:3]
	s_mov_b64 s[0:1], -1
	s_waitcnt vmcnt(0) lgkmcnt(0)
	v_cndmask_b32_e64 v2, 0, 1, s[2:3]
	v_readlane_b32 s2, v242, 0
	v_readlane_b32 s2, v242, 40
	v_readlane_b32 s3, v242, 1
	s_mulk_i32 s2, 0x4200
	v_cmp_ne_u32_e64 s[12:13], 1, v2
	v_writelane_b32 v242, s2, 0
	s_barrier
	s_nop 0
	v_writelane_b32 v242, s3, 1
	s_cbranch_vccnz .LBB0_917
	s_mov_b64 s[0:1], 0

.LFB_b3_noinv:
	s_mov_b64 s[0:1], exec
	v_readlane_b32 s2, v244, 4
	v_readlane_b32 s3, v244, 5
	s_and_b64 s[2:3], s[0:1], s[2:3]
	s_mov_b64 exec, s[2:3]
	s_cbranch_execz .LBB0_430
	v_readlane_b32 s4, v243, 10
	v_readlane_b32 s5, v243, 11
	v_readlane_b32 s2, v242, 40
	s_waitcnt vmcnt(0) expcnt(0) lgkmcnt(0)
	ds_read_b32 v4, v155 offset:16
	ds_read_b32 v2, v155 offset:20
	v_mov_b32_e32 v5, 1
	s_mul_i32 s2, s2, 3
	s_add_i32 s3, s2, 4
	s_add_i32 s2, s2, 3
	global_atomic_add v5, v155, v5, s[4:5] sc0
	s_add_u32 s6, s4, 0x2240
	s_addc_u32 s7, s5, 0
	s_mov_b32 s10, 0
	s_waitcnt lgkmcnt(0)
	v_mul_lo_u32 v6, v4, s3
	v_mul_lo_u32 v7, v2, s2
	s_waitcnt vmcnt(0)
	v_add_u32_e32 v5, 1, v5
	v_cmp_ne_u32_e32 vcc, v5, v6
	s_cbranch_vccnz .LFB_b3_poll
	s_mov_b64 s[12:13], exec
	s_mov_b64 exec, 0xffff
	v_mbcnt_lo_u32_b32 v8, -1, 0
	v_mov_b32_e32 v9, 1
	v_lshlrev_b32_e32 v8, 8, v8
	v_add_u32_e32 v8, 0x3640, v8
	global_atomic_add v8, v9, s[96:97]
	s_mov_b64 exec, s[12:13]

.LFB_b3_done:
	s_waitcnt vmcnt(0)
	s_branch .LBB0_430
